# FFN-up epilogue: n=0 and n=1 halves of each 16-byte output chunk stored together as one dwordx4 (8 stores per wave instead of 16)
# speedup vs baseline: 1.0152x; 1.0103x over previous
.Lffe_759:
	s_mov_b32 s14, 0xbf3a00e3
	v_fma_f32 v154, |v144|, s74, 1.0
	v_fma_f32 v201, |v145|, s74, 1.0
	v_mov_b64_e32 v[204:205], s[14:15]
	v_rcp_f32_e32 v200, v154
	v_rcp_f32_e32 v201, v201
	s_mov_b32 s14, 0x3f07dc22
	v_mul_f32_e32 v154, v144, v144
	v_pk_fma_f32 v[206:207], v[200:201], s[14:15], v[204:205] op_sel_hi:[1,0,0]
	v_mul_f32_e32 v154, 0xbf38aa3b, v154
	v_pk_fma_f32 v[206:207], v[200:201], v[206:207], s[16:17] op_sel_hi:[1,1,0]
	v_exp_f32_e32 v202, v154
	v_pk_fma_f32 v[206:207], v[200:201], v[206:207], s[18:19] op_sel_hi:[1,1,0]
	v_mul_f32_e32 v154, v145, v145
	v_pk_fma_f32 v[206:207], v[200:201], v[206:207], s[28:29] op_sel_hi:[1,1,0]
	v_mul_f32_e32 v154, 0xbf38aa3b, v154
	v_exp_f32_e32 v203, v154
	v_pk_mul_f32 v[200:201], v[200:201], v[206:207]
	v_cmp_gt_f32_e32 vcc, 0, v145
	v_pk_mul_f32 v[200:201], v[202:203], v[200:201]
	s_nop 0
	v_pk_mul_f32 v[202:203], v[144:145], v[200:201]
	v_pk_fma_f32 v[200:201], v[144:145], v[200:201], v[144:145] neg_lo:[1,0,0] neg_hi:[1,0,0]
	s_nop 0
	v_cndmask_b32_e32 v145, v201, v203, vcc
	v_cmp_gt_f32_e32 vcc, 0, v144
	s_nop 1
	v_cndmask_b32_e32 v144, v200, v202, vcc
	v_pk_mul_f32 v[144:145], v[148:149], v[144:145]
	v_cmp_gt_f32_e32 vcc, 0, v147
	v_cvt_pk_bf16_f32 v234, v144, v145
	v_fma_f32 v145, |v146|, s74, 1.0
	v_rcp_f32_e32 v148, v145
	v_fma_f32 v145, |v147|, s74, 1.0
	v_rcp_f32_e32 v149, v145
	v_mul_f32_e32 v145, v146, v146
	v_pk_fma_f32 v[202:203], v[148:149], s[14:15], v[204:205] op_sel_hi:[1,0,0]
	v_mul_f32_e32 v145, 0xbf38aa3b, v145
	v_pk_fma_f32 v[202:203], v[148:149], v[202:203], s[16:17] op_sel_hi:[1,1,0]
	v_exp_f32_e32 v200, v145
	v_pk_fma_f32 v[202:203], v[148:149], v[202:203], s[18:19] op_sel_hi:[1,1,0]
	v_mul_f32_e32 v145, v147, v147
	v_pk_fma_f32 v[202:203], v[148:149], v[202:203], s[28:29] op_sel_hi:[1,1,0]
	v_mul_f32_e32 v145, 0xbf38aa3b, v145
	v_exp_f32_e32 v201, v145
	v_pk_mul_f32 v[148:149], v[148:149], v[202:203]
	s_movk_i32 s14, 0x1600
	v_pk_mul_f32 v[148:149], v[200:201], v[148:149]
	s_nop 0
	v_pk_mul_f32 v[200:201], v[146:147], v[148:149]
	v_pk_fma_f32 v[148:149], v[146:147], v[148:149], v[146:147] neg_lo:[1,0,0] neg_hi:[1,0,0]
	s_nop 0
	v_cndmask_b32_e32 v147, v149, v201, vcc
	v_cmp_gt_f32_e32 vcc, 0, v146
	s_nop 1
	v_cndmask_b32_e32 v146, v148, v200, vcc
	v_pk_mul_f32 v[146:147], v[150:151], v[146:147]
	s_nop 0
	v_cvt_pk_bf16_f32 v235, v146, v147

.Lffe_765:
	s_mov_b32 s16, 0xbf3a00e3
	v_fma_f32 v144, |v136|, s74, 1.0
	v_fma_f32 v147, |v137|, s74, 1.0
	v_mov_b64_e32 v[150:151], s[16:17]
	v_rcp_f32_e32 v146, v144
	v_rcp_f32_e32 v147, v147
	s_mov_b32 s16, 0x3f07dc22
	v_mul_f32_e32 v144, v136, v136
	v_pk_fma_f32 v[208:209], v[146:147], s[16:17], v[150:151] op_sel_hi:[1,0,0]
	v_mul_f32_e32 v144, 0xbf38aa3b, v144
	v_pk_fma_f32 v[208:209], v[146:147], v[208:209], s[18:19] op_sel_hi:[1,1,0]
	v_exp_f32_e32 v148, v144
	v_pk_fma_f32 v[208:209], v[146:147], v[208:209], s[28:29] op_sel_hi:[1,1,0]
	v_mul_f32_e32 v144, v137, v137
	v_pk_fma_f32 v[208:209], v[146:147], v[208:209], s[54:55] op_sel_hi:[1,1,0]
	v_mul_f32_e32 v144, 0xbf38aa3b, v144
	v_exp_f32_e32 v149, v144
	v_pk_mul_f32 v[146:147], v[146:147], v[208:209]
	v_cmp_gt_f32_e32 vcc, 0, v137
	v_pk_mul_f32 v[146:147], v[148:149], v[146:147]
	s_nop 0
	v_pk_mul_f32 v[148:149], v[136:137], v[146:147]
	v_pk_fma_f32 v[146:147], v[136:137], v[146:147], v[136:137] neg_lo:[1,0,0] neg_hi:[1,0,0]
	s_nop 0
	v_cndmask_b32_e32 v137, v147, v149, vcc
	v_cmp_gt_f32_e32 vcc, 0, v136
	s_nop 1
	v_cndmask_b32_e32 v136, v146, v148, vcc
	v_pk_mul_f32 v[136:137], v[140:141], v[136:137]
	v_cmp_gt_f32_e32 vcc, 0, v139
	v_cvt_pk_bf16_f32 v236, v136, v137
	v_fma_f32 v137, |v138|, s74, 1.0
	v_rcp_f32_e32 v140, v137
	v_fma_f32 v137, |v139|, s74, 1.0
	v_rcp_f32_e32 v141, v137
	v_mul_f32_e32 v137, v138, v138
	v_pk_fma_f32 v[148:149], v[140:141], s[16:17], v[150:151] op_sel_hi:[1,0,0]
	v_mul_f32_e32 v137, 0xbf38aa3b, v137
	v_pk_fma_f32 v[148:149], v[140:141], v[148:149], s[18:19] op_sel_hi:[1,1,0]
	v_exp_f32_e32 v146, v137
	v_pk_fma_f32 v[148:149], v[140:141], v[148:149], s[28:29] op_sel_hi:[1,1,0]
	v_mul_f32_e32 v137, v139, v139
	v_pk_fma_f32 v[148:149], v[140:141], v[148:149], s[54:55] op_sel_hi:[1,1,0]
	v_mul_f32_e32 v137, 0xbf38aa3b, v137
	v_exp_f32_e32 v147, v137
	v_pk_mul_f32 v[140:141], v[140:141], v[148:149]
	s_movk_i32 s16, 0x1600
	v_pk_mul_f32 v[140:141], v[146:147], v[140:141]
	s_nop 0
	v_pk_mul_f32 v[146:147], v[138:139], v[140:141]
	v_pk_fma_f32 v[140:141], v[138:139], v[140:141], v[138:139] neg_lo:[1,0,0] neg_hi:[1,0,0]
	s_nop 0
	v_cndmask_b32_e32 v139, v141, v147, vcc
	v_cmp_gt_f32_e32 vcc, 0, v138
	s_nop 1
	v_cndmask_b32_e32 v138, v140, v146, vcc
	v_pk_mul_f32 v[138:139], v[142:143], v[138:139]
	s_nop 0
	v_cvt_pk_bf16_f32 v237, v138, v139

.Lffe_771:
	s_mov_b32 s18, 0xbf3a00e3
	v_fma_f32 v136, |v128|, s74, 1.0
	v_fma_f32 v137, |v129|, s74, 1.0
	v_mov_b64_e32 v[140:141], s[18:19]
	v_rcp_f32_e32 v136, v136
	v_rcp_f32_e32 v137, v137
	s_mov_b32 s18, 0x3f07dc22
	v_mul_f32_e32 v138, v128, v128
	v_pk_fma_f32 v[142:143], v[136:137], s[18:19], v[140:141] op_sel_hi:[1,0,0]
	v_mul_f32_e32 v139, v129, v129
	v_pk_fma_f32 v[142:143], v[136:137], v[142:143], s[60:61] op_sel_hi:[1,1,0]
	v_mul_f32_e32 v138, 0xbf38aa3b, v138
	v_pk_fma_f32 v[142:143], v[136:137], v[142:143], s[28:29] op_sel_hi:[1,1,0]
	v_mul_f32_e32 v139, 0xbf38aa3b, v139
	v_pk_fma_f32 v[142:143], v[136:137], v[142:143], s[64:65] op_sel_hi:[1,1,0]
	v_exp_f32_e32 v138, v138
	v_exp_f32_e32 v139, v139
	v_pk_mul_f32 v[136:137], v[136:137], v[142:143]
	v_cmp_gt_f32_e32 vcc, 0, v129
	v_pk_mul_f32 v[136:137], v[138:139], v[136:137]
	s_nop 0
	v_pk_mul_f32 v[138:139], v[128:129], v[136:137]
	v_pk_fma_f32 v[136:137], v[128:129], v[136:137], v[128:129] neg_lo:[1,0,0] neg_hi:[1,0,0]
	s_nop 0
	v_cndmask_b32_e32 v129, v137, v139, vcc
	v_cmp_gt_f32_e32 vcc, 0, v128
	s_nop 1
	v_cndmask_b32_e32 v128, v136, v138, vcc
	v_pk_mul_f32 v[128:129], v[132:133], v[128:129]
	v_cmp_gt_f32_e32 vcc, 0, v131
	v_cvt_pk_bf16_f32 v238, v128, v129
	v_fma_f32 v129, |v130|, s74, 1.0
	v_rcp_f32_e32 v132, v129
	v_fma_f32 v129, |v131|, s74, 1.0
	v_rcp_f32_e32 v133, v129
	v_mul_f32_e32 v129, v130, v130
	v_pk_fma_f32 v[138:139], v[132:133], s[18:19], v[140:141] op_sel_hi:[1,0,0]
	v_mul_f32_e32 v129, 0xbf38aa3b, v129
	v_pk_fma_f32 v[138:139], v[132:133], v[138:139], s[60:61] op_sel_hi:[1,1,0]
	v_exp_f32_e32 v136, v129
	v_pk_fma_f32 v[138:139], v[132:133], v[138:139], s[28:29] op_sel_hi:[1,1,0]
	v_mul_f32_e32 v129, v131, v131
	v_pk_fma_f32 v[138:139], v[132:133], v[138:139], s[64:65] op_sel_hi:[1,1,0]
	v_mul_f32_e32 v129, 0xbf38aa3b, v129
	v_exp_f32_e32 v137, v129
	v_pk_mul_f32 v[132:133], v[132:133], v[138:139]
	s_movk_i32 s18, 0x1600
	v_pk_mul_f32 v[132:133], v[136:137], v[132:133]
	s_nop 0
	v_pk_mul_f32 v[136:137], v[130:131], v[132:133]
	v_pk_fma_f32 v[132:133], v[130:131], v[132:133], v[130:131] neg_lo:[1,0,0] neg_hi:[1,0,0]
	s_nop 0
	v_cndmask_b32_e32 v131, v133, v137, vcc
	v_cmp_gt_f32_e32 vcc, 0, v130
	s_nop 1
	v_cndmask_b32_e32 v130, v132, v136, vcc
	v_pk_mul_f32 v[130:131], v[134:135], v[130:131]
	s_nop 0
	v_cvt_pk_bf16_f32 v239, v130, v131

.Lffe_777:
	s_mov_b32 s18, 0xbf3a00e3
	v_fma_f32 v136, |v128|, s74, 1.0
	v_fma_f32 v137, |v129|, s74, 1.0
	v_mov_b64_e32 v[140:141], s[18:19]
	v_rcp_f32_e32 v136, v136
	v_rcp_f32_e32 v137, v137
	s_mov_b32 s18, 0x3f07dc22
	v_mul_f32_e32 v138, v128, v128
	v_pk_fma_f32 v[142:143], v[136:137], s[18:19], v[140:141] op_sel_hi:[1,0,0]
	v_mul_f32_e32 v139, v129, v129
	v_pk_fma_f32 v[142:143], v[136:137], v[142:143], s[60:61] op_sel_hi:[1,1,0]
	v_mul_f32_e32 v138, 0xbf38aa3b, v138
	v_pk_fma_f32 v[142:143], v[136:137], v[142:143], s[28:29] op_sel_hi:[1,1,0]
	v_mul_f32_e32 v139, 0xbf38aa3b, v139
	v_pk_fma_f32 v[142:143], v[136:137], v[142:143], s[64:65] op_sel_hi:[1,1,0]
	v_exp_f32_e32 v138, v138
	v_exp_f32_e32 v139, v139
	v_pk_mul_f32 v[136:137], v[136:137], v[142:143]
	v_cmp_gt_f32_e32 vcc, 0, v129
	v_pk_mul_f32 v[136:137], v[138:139], v[136:137]
	s_nop 0
	v_pk_mul_f32 v[138:139], v[128:129], v[136:137]
	v_pk_fma_f32 v[136:137], v[128:129], v[136:137], v[128:129] neg_lo:[1,0,0] neg_hi:[1,0,0]
	s_nop 0
	v_cndmask_b32_e32 v129, v137, v139, vcc
	v_cmp_gt_f32_e32 vcc, 0, v128
	s_nop 1
	v_cndmask_b32_e32 v128, v136, v138, vcc
	v_pk_mul_f32 v[128:129], v[132:133], v[128:129]
	v_cmp_gt_f32_e32 vcc, 0, v131
	v_cvt_pk_bf16_f32 v240, v128, v129
	v_fma_f32 v129, |v130|, s74, 1.0
	v_rcp_f32_e32 v132, v129
	v_fma_f32 v129, |v131|, s74, 1.0
	v_rcp_f32_e32 v133, v129
	v_mul_f32_e32 v129, v130, v130
	v_pk_fma_f32 v[138:139], v[132:133], s[18:19], v[140:141] op_sel_hi:[1,0,0]
	v_mul_f32_e32 v129, 0xbf38aa3b, v129
	v_pk_fma_f32 v[138:139], v[132:133], v[138:139], s[60:61] op_sel_hi:[1,1,0]
	v_exp_f32_e32 v136, v129
	v_pk_fma_f32 v[138:139], v[132:133], v[138:139], s[28:29] op_sel_hi:[1,1,0]
	v_mul_f32_e32 v129, v131, v131
	v_pk_fma_f32 v[138:139], v[132:133], v[138:139], s[64:65] op_sel_hi:[1,1,0]
	v_mul_f32_e32 v129, 0xbf38aa3b, v129
	v_exp_f32_e32 v137, v129
	v_pk_mul_f32 v[132:133], v[132:133], v[138:139]
	s_movk_i32 s18, 0x1600
	v_pk_mul_f32 v[132:133], v[136:137], v[132:133]
	s_nop 0
	v_pk_mul_f32 v[136:137], v[130:131], v[132:133]
	v_pk_fma_f32 v[132:133], v[130:131], v[132:133], v[130:131] neg_lo:[1,0,0] neg_hi:[1,0,0]
	s_nop 0
	v_cndmask_b32_e32 v131, v133, v137, vcc
	v_cmp_gt_f32_e32 vcc, 0, v130
	s_nop 1
	v_cndmask_b32_e32 v130, v132, v136, vcc
	v_pk_mul_f32 v[130:131], v[134:135], v[130:131]
	s_nop 0
	v_cvt_pk_bf16_f32 v241, v130, v131

.Lffe_783:
	s_mov_b32 s18, 0xbf3a00e3
	v_fma_f32 v104, |v96|, s74, 1.0
	v_fma_f32 v107, |v97|, s74, 1.0
	v_mov_b64_e32 v[114:115], s[18:19]
	v_rcp_f32_e32 v106, v104
	v_rcp_f32_e32 v107, v107
	s_mov_b32 s18, 0x3f07dc22
	v_mul_f32_e32 v104, v96, v96
	v_pk_fma_f32 v[136:137], v[106:107], s[18:19], v[114:115] op_sel_hi:[1,0,0]
	v_mul_f32_e32 v104, 0xbf38aa3b, v104
	v_pk_fma_f32 v[136:137], v[106:107], v[136:137], s[60:61] op_sel_hi:[1,1,0]
	v_exp_f32_e32 v112, v104
	v_pk_fma_f32 v[136:137], v[106:107], v[136:137], s[28:29] op_sel_hi:[1,1,0]
	v_mul_f32_e32 v104, v97, v97
	v_pk_fma_f32 v[136:137], v[106:107], v[136:137], s[64:65] op_sel_hi:[1,1,0]
	v_mul_f32_e32 v104, 0xbf38aa3b, v104
	v_exp_f32_e32 v113, v104
	v_pk_mul_f32 v[106:107], v[106:107], v[136:137]
	v_cmp_gt_f32_e32 vcc, 0, v97
	v_pk_mul_f32 v[106:107], v[112:113], v[106:107]
	s_nop 0
	v_pk_mul_f32 v[112:113], v[96:97], v[106:107]
	v_pk_fma_f32 v[106:107], v[96:97], v[106:107], v[96:97] neg_lo:[1,0,0] neg_hi:[1,0,0]
	s_nop 0
	v_cndmask_b32_e32 v97, v107, v113, vcc
	v_cmp_gt_f32_e32 vcc, 0, v96
	s_nop 1
	v_cndmask_b32_e32 v96, v106, v112, vcc
	v_pk_mul_f32 v[96:97], v[100:101], v[96:97]
	v_cmp_gt_f32_e32 vcc, 0, v99
	v_cvt_pk_bf16_f32 v202, v96, v97
	v_fma_f32 v97, |v98|, s74, 1.0
	v_rcp_f32_e32 v100, v97
	v_fma_f32 v97, |v99|, s74, 1.0
	v_rcp_f32_e32 v101, v97
	v_mul_f32_e32 v97, v98, v98
	v_pk_fma_f32 v[112:113], v[100:101], s[18:19], v[114:115] op_sel_hi:[1,0,0]
	v_mul_f32_e32 v97, 0xbf38aa3b, v97
	v_pk_fma_f32 v[112:113], v[100:101], v[112:113], s[60:61] op_sel_hi:[1,1,0]
	v_exp_f32_e32 v106, v97
	v_pk_fma_f32 v[112:113], v[100:101], v[112:113], s[28:29] op_sel_hi:[1,1,0]
	v_mul_f32_e32 v97, v99, v99
	v_pk_fma_f32 v[112:113], v[100:101], v[112:113], s[64:65] op_sel_hi:[1,1,0]
	v_mul_f32_e32 v97, 0xbf38aa3b, v97
	v_exp_f32_e32 v107, v97
	v_pk_mul_f32 v[100:101], v[100:101], v[112:113]
	s_movk_i32 s18, 0x1600
	v_pk_mul_f32 v[100:101], v[106:107], v[100:101]
	s_nop 0
	v_pk_mul_f32 v[106:107], v[98:99], v[100:101]
	v_pk_fma_f32 v[100:101], v[98:99], v[100:101], v[98:99] neg_lo:[1,0,0] neg_hi:[1,0,0]
	s_nop 0
	v_cndmask_b32_e32 v99, v101, v107, vcc
	v_cmp_gt_f32_e32 vcc, 0, v98
	s_nop 1
	v_cndmask_b32_e32 v98, v100, v106, vcc
	v_pk_mul_f32 v[98:99], v[102:103], v[98:99]
	s_nop 0
	v_cvt_pk_bf16_f32 v203, v98, v99

.Lffe_789:
	v_fma_f32 v96, |v72|, s74, 1.0
	v_fma_f32 v99, |v73|, s74, 1.0
	v_rcp_f32_e32 v98, v96
	v_rcp_f32_e32 v99, v99
	v_mul_f32_e32 v96, v72, v72
	v_pk_fma_f32 v[142:143], v[98:99], s[64:65], v[102:103] op_sel_hi:[1,0,0]
	v_mul_f32_e32 v96, 0xbf38aa3b, v96
	v_pk_fma_f32 v[142:143], v[98:99], v[142:143], s[66:67] op_sel_hi:[1,1,0]
	v_exp_f32_e32 v100, v96
	v_pk_fma_f32 v[142:143], v[98:99], v[142:143], s[28:29] op_sel_hi:[1,1,0]
	v_mul_f32_e32 v96, v73, v73
	v_pk_fma_f32 v[142:143], v[98:99], v[142:143], s[76:77] op_sel_hi:[1,1,0]
	v_mul_f32_e32 v96, 0xbf38aa3b, v96
	v_exp_f32_e32 v101, v96
	v_pk_mul_f32 v[98:99], v[98:99], v[142:143]
	v_cmp_gt_f32_e32 vcc, 0, v73
	v_pk_mul_f32 v[98:99], v[100:101], v[98:99]
	s_nop 0
	v_pk_mul_f32 v[100:101], v[72:73], v[98:99]
	v_pk_fma_f32 v[98:99], v[72:73], v[98:99], v[72:73] neg_lo:[1,0,0] neg_hi:[1,0,0]
	s_nop 0
	v_cndmask_b32_e32 v73, v99, v101, vcc
	v_cmp_gt_f32_e32 vcc, 0, v72
	s_nop 1
	v_cndmask_b32_e32 v72, v98, v100, vcc
	v_pk_mul_f32 v[72:73], v[76:77], v[72:73]
	v_cmp_gt_f32_e32 vcc, 0, v75
	v_cvt_pk_bf16_f32 v204, v72, v73
	v_fma_f32 v73, |v74|, s74, 1.0
	v_rcp_f32_e32 v76, v73
	v_fma_f32 v73, |v75|, s74, 1.0
	v_rcp_f32_e32 v77, v73
	v_mul_f32_e32 v73, v74, v74
	v_pk_fma_f32 v[100:101], v[76:77], s[64:65], v[102:103] op_sel_hi:[1,0,0]
	v_mul_f32_e32 v73, 0xbf38aa3b, v73
	v_pk_fma_f32 v[100:101], v[76:77], v[100:101], s[66:67] op_sel_hi:[1,1,0]
	v_exp_f32_e32 v98, v73
	v_pk_fma_f32 v[100:101], v[76:77], v[100:101], s[28:29] op_sel_hi:[1,1,0]
	v_mul_f32_e32 v73, v75, v75
	v_pk_fma_f32 v[100:101], v[76:77], v[100:101], s[76:77] op_sel_hi:[1,1,0]
	v_mul_f32_e32 v73, 0xbf38aa3b, v73
	v_exp_f32_e32 v99, v73
	v_pk_mul_f32 v[76:77], v[76:77], v[100:101]
	s_movk_i32 s64, 0x1600
	v_pk_mul_f32 v[76:77], v[98:99], v[76:77]
	s_nop 0
	v_pk_mul_f32 v[98:99], v[74:75], v[76:77]
	v_pk_fma_f32 v[76:77], v[74:75], v[76:77], v[74:75] neg_lo:[1,0,0] neg_hi:[1,0,0]
	s_nop 0
	v_cndmask_b32_e32 v75, v77, v99, vcc
	v_cmp_gt_f32_e32 vcc, 0, v74
	s_nop 1
	v_cndmask_b32_e32 v74, v76, v98, vcc
	v_pk_mul_f32 v[74:75], v[78:79], v[74:75]
	s_nop 0
	v_cvt_pk_bf16_f32 v205, v74, v75

.Lffe_795:
	v_fma_f32 v72, |v64|, s74, 1.0
	v_fma_f32 v73, |v65|, s74, 1.0
	v_rcp_f32_e32 v72, v72
	v_rcp_f32_e32 v73, v73
	s_mov_b32 s92, 0x3f35f0e3
	v_pk_fma_f32 v[78:79], v[72:73], s[66:67], v[76:77] op_sel_hi:[1,0,0]
	v_mul_f32_e32 v74, v64, v64
	v_pk_fma_f32 v[78:79], v[72:73], v[78:79], s[92:93] op_sel_hi:[1,1,0]
	v_mul_f32_e32 v75, v65, v65
	v_pk_fma_f32 v[78:79], v[72:73], v[78:79], s[28:29] op_sel_hi:[1,1,0]
	v_mul_f32_e32 v74, 0xbf38aa3b, v74
	v_pk_fma_f32 v[78:79], v[72:73], v[78:79], s[76:77] op_sel_hi:[1,1,0]
	v_mul_f32_e32 v75, 0xbf38aa3b, v75
	v_exp_f32_e32 v74, v74
	v_exp_f32_e32 v75, v75
	v_pk_mul_f32 v[72:73], v[72:73], v[78:79]
	v_cmp_gt_f32_e32 vcc, 0, v65
	v_pk_mul_f32 v[72:73], v[74:75], v[72:73]
	s_nop 0
	v_pk_mul_f32 v[74:75], v[64:65], v[72:73]
	v_pk_fma_f32 v[72:73], v[64:65], v[72:73], v[64:65] neg_lo:[1,0,0] neg_hi:[1,0,0]
	s_nop 0
	v_cndmask_b32_e32 v65, v73, v75, vcc
	v_cmp_gt_f32_e32 vcc, 0, v64
	s_nop 1
	v_cndmask_b32_e32 v64, v72, v74, vcc
	v_pk_mul_f32 v[64:65], v[68:69], v[64:65]
	v_cmp_gt_f32_e32 vcc, 0, v67
	v_cvt_pk_bf16_f32 v206, v64, v65
	v_fma_f32 v65, |v66|, s74, 1.0
	v_rcp_f32_e32 v68, v65
	v_fma_f32 v65, |v67|, s74, 1.0
	v_rcp_f32_e32 v69, v65
	v_mul_f32_e32 v65, v66, v66
	v_pk_fma_f32 v[74:75], v[68:69], s[66:67], v[76:77] op_sel_hi:[1,0,0]
	v_mul_f32_e32 v65, 0xbf38aa3b, v65
	v_pk_fma_f32 v[74:75], v[68:69], v[74:75], s[92:93] op_sel_hi:[1,1,0]
	v_exp_f32_e32 v72, v65
	v_pk_fma_f32 v[74:75], v[68:69], v[74:75], s[28:29] op_sel_hi:[1,1,0]
	v_mul_f32_e32 v65, v67, v67
	v_pk_fma_f32 v[74:75], v[68:69], v[74:75], s[76:77] op_sel_hi:[1,1,0]
	v_mul_f32_e32 v65, 0xbf38aa3b, v65
	v_exp_f32_e32 v73, v65
	v_pk_mul_f32 v[68:69], v[68:69], v[74:75]
	s_movk_i32 s66, 0x1600
	v_pk_mul_f32 v[68:69], v[72:73], v[68:69]
	s_nop 0
	v_pk_mul_f32 v[72:73], v[66:67], v[68:69]
	v_pk_fma_f32 v[68:69], v[66:67], v[68:69], v[66:67] neg_lo:[1,0,0] neg_hi:[1,0,0]
	s_nop 0
	v_cndmask_b32_e32 v67, v69, v73, vcc
	v_cmp_gt_f32_e32 vcc, 0, v66
	s_nop 1
	v_cndmask_b32_e32 v66, v68, v72, vcc
	v_pk_mul_f32 v[66:67], v[70:71], v[66:67]
	s_nop 0
	v_cvt_pk_bf16_f32 v207, v66, v67

.Lffe_801:
	s_mov_b32 s70, 0xbf3a00e3
	v_fma_f32 v72, |v64|, s74, 1.0
	v_fma_f32 v73, |v65|, s74, 1.0
	v_mov_b64_e32 v[76:77], s[70:71]
	v_rcp_f32_e32 v72, v72
	v_rcp_f32_e32 v73, v73
	s_mov_b32 s70, 0x3f07dc22
	v_mul_f32_e32 v74, v64, v64
	v_pk_fma_f32 v[78:79], v[72:73], s[70:71], v[76:77] op_sel_hi:[1,0,0]
	v_mul_f32_e32 v75, v65, v65
	v_pk_fma_f32 v[78:79], v[72:73], v[78:79], s[28:29] op_sel_hi:[1,1,0]
	v_mul_f32_e32 v74, 0xbf38aa3b, v74
	v_pk_fma_f32 v[78:79], v[72:73], v[78:79], s[76:77] op_sel_hi:[1,1,0]
	v_mul_f32_e32 v75, 0xbf38aa3b, v75
	v_pk_fma_f32 v[78:79], v[72:73], v[78:79], s[8:9] op_sel_hi:[1,1,0]
	v_exp_f32_e32 v74, v74
	v_exp_f32_e32 v75, v75
	v_pk_mul_f32 v[72:73], v[72:73], v[78:79]
	v_cmp_gt_f32_e32 vcc, 0, v65
	v_pk_mul_f32 v[72:73], v[74:75], v[72:73]
	s_nop 0
	v_pk_mul_f32 v[74:75], v[64:65], v[72:73]
	v_pk_fma_f32 v[72:73], v[64:65], v[72:73], v[64:65] neg_lo:[1,0,0] neg_hi:[1,0,0]
	s_nop 0
	v_cndmask_b32_e32 v65, v73, v75, vcc
	v_cmp_gt_f32_e32 vcc, 0, v64
	s_nop 1
	v_cndmask_b32_e32 v64, v72, v74, vcc
	v_pk_mul_f32 v[64:65], v[68:69], v[64:65]
	v_cmp_gt_f32_e32 vcc, 0, v67
	v_cvt_pk_bf16_f32 v208, v64, v65
	v_fma_f32 v65, |v66|, s74, 1.0
	v_rcp_f32_e32 v68, v65
	v_fma_f32 v65, |v67|, s74, 1.0
	v_rcp_f32_e32 v69, v65
	v_mul_f32_e32 v65, v66, v66
	v_pk_fma_f32 v[74:75], v[68:69], s[70:71], v[76:77] op_sel_hi:[1,0,0]
	v_mul_f32_e32 v65, 0xbf38aa3b, v65
	v_pk_fma_f32 v[74:75], v[68:69], v[74:75], s[28:29] op_sel_hi:[1,1,0]
	v_exp_f32_e32 v72, v65
	v_pk_fma_f32 v[74:75], v[68:69], v[74:75], s[76:77] op_sel_hi:[1,1,0]
	v_mul_f32_e32 v65, v67, v67
	v_pk_fma_f32 v[74:75], v[68:69], v[74:75], s[8:9] op_sel_hi:[1,1,0]
	v_mul_f32_e32 v65, 0xbf38aa3b, v65
	v_exp_f32_e32 v73, v65
	v_pk_mul_f32 v[68:69], v[68:69], v[74:75]
	s_movk_i32 s70, 0x1600
	v_pk_mul_f32 v[68:69], v[72:73], v[68:69]
	v_readlane_b32 s70, v242, 0
	v_pk_mul_f32 v[72:73], v[66:67], v[68:69]
	v_pk_fma_f32 v[68:69], v[66:67], v[68:69], v[66:67] neg_lo:[1,0,0] neg_hi:[1,0,0]
	v_readlane_b32 s71, v242, 1
	v_cndmask_b32_e32 v67, v69, v73, vcc
	v_cmp_gt_f32_e32 vcc, 0, v66
	s_nop 1
	v_cndmask_b32_e32 v66, v68, v72, vcc
	v_pk_mul_f32 v[66:67], v[70:71], v[66:67]
	s_nop 0
	v_cvt_pk_bf16_f32 v209, v66, v67

.LBB0_805:
	v_xor_b32_e32 v59, 0x80000000, v75
	v_xor_b32_e32 v58, 0x80000000, v74
	v_xor_b32_e32 v57, 0x80000000, v67
	v_xor_b32_e32 v56, 0x80000000, v66
	s_and_saveexec_b64 s[48:49], s[50:51]
	s_cbranch_execz .LBB0_807
	s_cmp_ge_i32 s25, s24
	v_pk_fma_f32 v[52:53], v[72:73], v[120:121], v[52:53]
	s_cselect_b64 s[50:51], -1, 0
	v_pk_fma_f32 v[54:55], v[74:75], v[122:123], v[54:55]
	v_pk_add_f32 v[52:53], v[76:77], v[52:53]
	v_pk_fma_f32 v[48:49], v[64:65], v[108:109], v[48:49]
	v_pk_add_f32 v[54:55], v[78:79], v[54:55]
	v_pk_fma_f32 v[50:51], v[66:67], v[110:111], v[50:51]
	v_pk_add_f32 v[48:49], v[68:69], v[48:49]
	v_pk_add_f32 v[50:51], v[70:71], v[50:51]
	s_mov_b32 s28, 0x3f35f0e3
	s_mov_b32 s76, 0xbe11a98e
	s_mov_b32 s8, 0x3e027906
	v_mov_b64_e32 v[148:149], v[234:235]
	s_cmp_eq_u64 s[50:51], 0
	s_cbranch_scc1 .Lffe_807
	v_cmp_eq_u32_e32 vcc, s37, v229
	v_pk_fma_f32 v[62:63], v[72:73], v[120:121], v[52:53] neg_lo:[1,0,0] neg_hi:[1,0,0]
	s_nop 0
	s_and_b64 vcc, s[50:51], vcc
	v_pk_fma_f32 v[60:61], v[58:59], v[122:123], v[54:55]
	v_cndmask_b32_e32 v53, v53, v63, vcc
	v_cndmask_b32_e32 v52, v52, v62, vcc
	v_pk_fma_f32 v[62:63], v[64:65], v[108:109], v[48:49] neg_lo:[1,0,0] neg_hi:[1,0,0]
	v_cndmask_b32_e32 v55, v55, v61, vcc
	v_cndmask_b32_e32 v54, v54, v60, vcc
	v_pk_fma_f32 v[60:61], v[56:57], v[110:111], v[50:51]
	v_cndmask_b32_e32 v49, v49, v63, vcc
	v_cndmask_b32_e32 v48, v48, v62, vcc
	v_cndmask_b32_e32 v51, v51, v61, vcc
	v_cndmask_b32_e32 v50, v50, v60, vcc
.Lffe_807:
	s_mov_b32 s50, 0xbf3a00e3
	v_fma_f32 v60, |v48|, s74, 1.0
	v_fma_f32 v61, |v49|, s74, 1.0
	v_mov_b64_e32 v[108:109], s[50:51]
	v_rcp_f32_e32 v60, v60
	v_rcp_f32_e32 v61, v61
	s_mov_b32 s50, 0x3f07dc22
	v_mul_f32_e32 v62, v48, v48
	v_pk_fma_f32 v[110:111], v[60:61], s[50:51], v[108:109] op_sel_hi:[1,0,0]
	v_mul_f32_e32 v63, v49, v49
	v_pk_fma_f32 v[110:111], v[60:61], v[110:111], s[28:29] op_sel_hi:[1,1,0]
	v_mul_f32_e32 v62, 0xbf38aa3b, v62
	v_pk_fma_f32 v[110:111], v[60:61], v[110:111], s[76:77] op_sel_hi:[1,1,0]
	v_mul_f32_e32 v63, 0xbf38aa3b, v63
	v_pk_fma_f32 v[110:111], v[60:61], v[110:111], s[8:9] op_sel_hi:[1,1,0]
	v_exp_f32_e32 v62, v62
	v_exp_f32_e32 v63, v63
	v_pk_mul_f32 v[60:61], v[60:61], v[110:111]
	v_cmp_gt_f32_e32 vcc, 0, v49
	v_pk_mul_f32 v[60:61], v[62:63], v[60:61]
	s_nop 0
	v_pk_mul_f32 v[62:63], v[48:49], v[60:61]
	v_pk_fma_f32 v[60:61], v[48:49], v[60:61], v[48:49] neg_lo:[1,0,0] neg_hi:[1,0,0]
	s_nop 0
	v_cndmask_b32_e32 v49, v61, v63, vcc
	v_cmp_gt_f32_e32 vcc, 0, v48
	s_nop 1
	v_cndmask_b32_e32 v48, v60, v62, vcc
	v_pk_mul_f32 v[48:49], v[52:53], v[48:49]
	v_cmp_gt_f32_e32 vcc, 0, v51
	v_cvt_pk_bf16_f32 v150, v48, v49
	v_fma_f32 v49, |v50|, s74, 1.0
	v_rcp_f32_e32 v52, v49
	v_fma_f32 v49, |v51|, s74, 1.0
	v_rcp_f32_e32 v53, v49
	v_mul_f32_e32 v49, v50, v50
	v_pk_fma_f32 v[62:63], v[52:53], s[50:51], v[108:109] op_sel_hi:[1,0,0]
	v_mul_f32_e32 v49, 0xbf38aa3b, v49
	v_pk_fma_f32 v[62:63], v[52:53], v[62:63], s[28:29] op_sel_hi:[1,1,0]
	v_exp_f32_e32 v60, v49
	v_pk_fma_f32 v[62:63], v[52:53], v[62:63], s[76:77] op_sel_hi:[1,1,0]
	v_mul_f32_e32 v49, v51, v51
	v_pk_fma_f32 v[62:63], v[52:53], v[62:63], s[8:9] op_sel_hi:[1,1,0]
	v_mul_f32_e32 v49, 0xbf38aa3b, v49
	v_exp_f32_e32 v61, v49
	v_pk_mul_f32 v[52:53], v[52:53], v[62:63]
	s_movk_i32 s50, 0x1600
	v_pk_mul_f32 v[52:53], v[60:61], v[52:53]
	s_nop 0
	v_pk_mul_f32 v[60:61], v[50:51], v[52:53]
	v_pk_fma_f32 v[52:53], v[50:51], v[52:53], v[50:51] neg_lo:[1,0,0] neg_hi:[1,0,0]
	s_nop 0
	v_cndmask_b32_e32 v51, v53, v61, vcc
	v_cmp_gt_f32_e32 vcc, 0, v50
	s_nop 1
	v_cndmask_b32_e32 v50, v52, v60, vcc
	v_pk_mul_f32 v[50:51], v[54:55], v[50:51]
	s_nop 0
	v_cvt_pk_bf16_f32 v151, v50, v51
	v_mad_u32_u24 v50, v155, s50, v153
	global_store_dwordx4 v50, v[148:151], s[26:27]

.LBB0_811:
	s_and_saveexec_b64 s[48:49], s[12:13]
	s_cbranch_execz .LBB0_813
	s_cmp_lt_i32 s23, s35
	s_cselect_b64 s[12:13], -1, 0
	s_cmp_ge_i32 s23, s24
	s_cselect_b64 s[50:51], -1, 0
	v_pk_fma_f32 v[44:45], v[72:73], v[116:117], v[44:45]
	s_and_b64 s[12:13], s[12:13], s[50:51]
	v_pk_fma_f32 v[46:47], v[74:75], v[118:119], v[46:47]
	v_pk_add_f32 v[44:45], v[76:77], v[44:45]
	v_pk_fma_f32 v[40:41], v[64:65], v[112:113], v[40:41]
	v_pk_add_f32 v[46:47], v[78:79], v[46:47]
	v_pk_fma_f32 v[42:43], v[66:67], v[114:115], v[42:43]
	v_pk_add_f32 v[40:41], v[68:69], v[40:41]
	v_pk_add_f32 v[42:43], v[70:71], v[42:43]
	s_mov_b32 s28, 0x3f35f0e3
	s_mov_b32 s50, 0xbe11a98e
	s_mov_b32 s8, 0x3e027906
	v_mov_b64_e32 v[148:149], v[236:237]
	s_cmp_eq_u64 s[12:13], 0
	s_cbranch_scc1 .Lffe_813
	v_cmp_eq_u32_e32 vcc, s37, v228
	v_pk_fma_f32 v[50:51], v[72:73], v[116:117], v[44:45] neg_lo:[1,0,0] neg_hi:[1,0,0]
	s_nop 0
	s_and_b64 vcc, s[12:13], vcc
	v_pk_fma_f32 v[48:49], v[58:59], v[118:119], v[46:47]
	v_cndmask_b32_e32 v45, v45, v51, vcc
	v_cndmask_b32_e32 v44, v44, v50, vcc
	v_pk_fma_f32 v[50:51], v[64:65], v[112:113], v[40:41] neg_lo:[1,0,0] neg_hi:[1,0,0]
	v_cndmask_b32_e32 v47, v47, v49, vcc
	v_cndmask_b32_e32 v46, v46, v48, vcc
	v_pk_fma_f32 v[48:49], v[56:57], v[114:115], v[42:43]
	v_cndmask_b32_e32 v41, v41, v51, vcc
	v_cndmask_b32_e32 v40, v40, v50, vcc
	v_cndmask_b32_e32 v43, v43, v49, vcc
	v_cndmask_b32_e32 v42, v42, v48, vcc
.Lffe_813:
	s_mov_b32 s12, 0xbf3a00e3
	v_fma_f32 v48, |v40|, s74, 1.0
	v_fma_f32 v49, |v41|, s74, 1.0
	v_mov_b64_e32 v[52:53], s[12:13]
	v_rcp_f32_e32 v48, v48
	v_rcp_f32_e32 v49, v49
	s_mov_b32 s12, 0x3f07dc22
	v_mul_f32_e32 v50, v40, v40
	v_pk_fma_f32 v[54:55], v[48:49], s[12:13], v[52:53] op_sel_hi:[1,0,0]
	v_mul_f32_e32 v51, v41, v41
	v_pk_fma_f32 v[54:55], v[48:49], v[54:55], s[28:29] op_sel_hi:[1,1,0]
	v_mul_f32_e32 v50, 0xbf38aa3b, v50
	v_pk_fma_f32 v[54:55], v[48:49], v[54:55], s[50:51] op_sel_hi:[1,1,0]
	v_mul_f32_e32 v51, 0xbf38aa3b, v51
	v_pk_fma_f32 v[54:55], v[48:49], v[54:55], s[8:9] op_sel_hi:[1,1,0]
	v_exp_f32_e32 v50, v50
	v_exp_f32_e32 v51, v51
	v_pk_mul_f32 v[48:49], v[48:49], v[54:55]
	v_cmp_gt_f32_e32 vcc, 0, v41
	v_pk_mul_f32 v[48:49], v[50:51], v[48:49]
	s_nop 0
	v_pk_mul_f32 v[50:51], v[40:41], v[48:49]
	v_pk_fma_f32 v[48:49], v[40:41], v[48:49], v[40:41] neg_lo:[1,0,0] neg_hi:[1,0,0]
	s_nop 0
	v_cndmask_b32_e32 v41, v49, v51, vcc
	v_cmp_gt_f32_e32 vcc, 0, v40
	s_nop 1
	v_cndmask_b32_e32 v40, v48, v50, vcc
	v_pk_mul_f32 v[40:41], v[44:45], v[40:41]
	v_cmp_gt_f32_e32 vcc, 0, v43
	v_cvt_pk_bf16_f32 v150, v40, v41
	v_fma_f32 v41, |v42|, s74, 1.0
	v_rcp_f32_e32 v44, v41
	v_fma_f32 v41, |v43|, s74, 1.0
	v_rcp_f32_e32 v45, v41
	v_mul_f32_e32 v41, v42, v42
	v_pk_fma_f32 v[50:51], v[44:45], s[12:13], v[52:53] op_sel_hi:[1,0,0]
	v_mul_f32_e32 v41, 0xbf38aa3b, v41
	v_pk_fma_f32 v[50:51], v[44:45], v[50:51], s[28:29] op_sel_hi:[1,1,0]
	v_exp_f32_e32 v48, v41
	v_pk_fma_f32 v[50:51], v[44:45], v[50:51], s[50:51] op_sel_hi:[1,1,0]
	v_mul_f32_e32 v41, v43, v43
	v_pk_fma_f32 v[50:51], v[44:45], v[50:51], s[8:9] op_sel_hi:[1,1,0]
	v_mul_f32_e32 v41, 0xbf38aa3b, v41
	v_exp_f32_e32 v49, v41
	v_pk_mul_f32 v[44:45], v[44:45], v[50:51]
	s_movk_i32 s12, 0x1600
	v_pk_mul_f32 v[44:45], v[48:49], v[44:45]
	s_nop 0
	v_pk_mul_f32 v[48:49], v[42:43], v[44:45]
	v_pk_fma_f32 v[44:45], v[42:43], v[44:45], v[42:43] neg_lo:[1,0,0] neg_hi:[1,0,0]
	s_nop 0
	v_cndmask_b32_e32 v43, v45, v49, vcc
	v_cmp_gt_f32_e32 vcc, 0, v42
	s_nop 1
	v_cndmask_b32_e32 v42, v44, v48, vcc
	v_pk_mul_f32 v[42:43], v[46:47], v[42:43]
	s_nop 0
	v_cvt_pk_bf16_f32 v151, v42, v43
	v_mad_u32_u24 v42, v145, s12, v153
	global_store_dwordx4 v42, v[148:151], s[26:27]

.LBB0_817:
	s_and_saveexec_b64 s[12:13], s[14:15]
	s_cbranch_execz .LBB0_819
	s_cmp_lt_i32 s67, s35
	s_cselect_b64 s[14:15], -1, 0
	s_cmp_ge_i32 s67, s24
	s_cselect_b64 s[48:49], -1, 0
	v_pk_fma_f32 v[36:37], v[72:73], v[102:103], v[36:37]
	s_and_b64 s[14:15], s[14:15], s[48:49]
	v_pk_fma_f32 v[38:39], v[74:75], v[106:107], v[38:39]
	v_pk_add_f32 v[36:37], v[76:77], v[36:37]
	v_pk_fma_f32 v[32:33], v[64:65], v[98:99], v[32:33]
	v_pk_add_f32 v[38:39], v[78:79], v[38:39]
	v_pk_fma_f32 v[34:35], v[66:67], v[100:101], v[34:35]
	v_pk_add_f32 v[32:33], v[68:69], v[32:33]
	v_pk_add_f32 v[34:35], v[70:71], v[34:35]
	s_mov_b32 s28, 0x3f35f0e3
	s_mov_b32 s48, 0xbe11a98e
	s_mov_b32 s8, 0x3e027906
	v_mov_b64_e32 v[148:149], v[238:239]
	s_cmp_eq_u64 s[14:15], 0
	s_cbranch_scc1 .Lffe_819
	v_cmp_eq_u32_e32 vcc, s37, v211
	v_pk_fma_f32 v[42:43], v[72:73], v[102:103], v[36:37] neg_lo:[1,0,0] neg_hi:[1,0,0]
	s_nop 0
	s_and_b64 vcc, s[14:15], vcc
	v_pk_fma_f32 v[40:41], v[58:59], v[106:107], v[38:39]
	v_cndmask_b32_e32 v37, v37, v43, vcc
	v_cndmask_b32_e32 v36, v36, v42, vcc
	v_pk_fma_f32 v[42:43], v[64:65], v[98:99], v[32:33] neg_lo:[1,0,0] neg_hi:[1,0,0]
	v_cndmask_b32_e32 v39, v39, v41, vcc
	v_cndmask_b32_e32 v38, v38, v40, vcc
	v_pk_fma_f32 v[40:41], v[56:57], v[100:101], v[34:35]
	v_cndmask_b32_e32 v33, v33, v43, vcc
	v_cndmask_b32_e32 v32, v32, v42, vcc
	v_cndmask_b32_e32 v35, v35, v41, vcc
	v_cndmask_b32_e32 v34, v34, v40, vcc
.Lffe_819:
	s_mov_b32 s14, 0xbf3a00e3
	v_fma_f32 v40, |v32|, s74, 1.0
	v_fma_f32 v41, |v33|, s74, 1.0
	v_mov_b64_e32 v[44:45], s[14:15]
	v_rcp_f32_e32 v40, v40
	v_rcp_f32_e32 v41, v41
	s_mov_b32 s14, 0x3f07dc22
	v_mul_f32_e32 v42, v32, v32
	v_pk_fma_f32 v[46:47], v[40:41], s[14:15], v[44:45] op_sel_hi:[1,0,0]
	v_mul_f32_e32 v43, v33, v33
	v_pk_fma_f32 v[46:47], v[40:41], v[46:47], s[28:29] op_sel_hi:[1,1,0]
	v_mul_f32_e32 v42, 0xbf38aa3b, v42
	v_pk_fma_f32 v[46:47], v[40:41], v[46:47], s[48:49] op_sel_hi:[1,1,0]
	v_mul_f32_e32 v43, 0xbf38aa3b, v43
	v_pk_fma_f32 v[46:47], v[40:41], v[46:47], s[8:9] op_sel_hi:[1,1,0]
	v_exp_f32_e32 v42, v42
	v_exp_f32_e32 v43, v43
	v_pk_mul_f32 v[40:41], v[40:41], v[46:47]
	v_cmp_gt_f32_e32 vcc, 0, v33
	v_pk_mul_f32 v[40:41], v[42:43], v[40:41]
	s_nop 0
	v_pk_mul_f32 v[42:43], v[32:33], v[40:41]
	v_pk_fma_f32 v[40:41], v[32:33], v[40:41], v[32:33] neg_lo:[1,0,0] neg_hi:[1,0,0]
	s_nop 0
	v_cndmask_b32_e32 v33, v41, v43, vcc
	v_cmp_gt_f32_e32 vcc, 0, v32
	s_nop 1
	v_cndmask_b32_e32 v32, v40, v42, vcc
	v_pk_mul_f32 v[32:33], v[36:37], v[32:33]
	v_cmp_gt_f32_e32 vcc, 0, v35
	v_cvt_pk_bf16_f32 v150, v32, v33
	v_fma_f32 v33, |v34|, s74, 1.0
	v_rcp_f32_e32 v36, v33
	v_fma_f32 v33, |v35|, s74, 1.0
	v_rcp_f32_e32 v37, v33
	v_mul_f32_e32 v33, v34, v34
	v_pk_fma_f32 v[42:43], v[36:37], s[14:15], v[44:45] op_sel_hi:[1,0,0]
	v_mul_f32_e32 v33, 0xbf38aa3b, v33
	v_pk_fma_f32 v[42:43], v[36:37], v[42:43], s[28:29] op_sel_hi:[1,1,0]
	v_exp_f32_e32 v40, v33
	v_pk_fma_f32 v[42:43], v[36:37], v[42:43], s[48:49] op_sel_hi:[1,1,0]
	v_mul_f32_e32 v33, v35, v35
	v_pk_fma_f32 v[42:43], v[36:37], v[42:43], s[8:9] op_sel_hi:[1,1,0]
	v_mul_f32_e32 v33, 0xbf38aa3b, v33
	v_exp_f32_e32 v41, v33
	v_pk_mul_f32 v[36:37], v[36:37], v[42:43]
	s_movk_i32 s14, 0x1600
	v_pk_mul_f32 v[36:37], v[40:41], v[36:37]
	s_nop 0
	v_pk_mul_f32 v[40:41], v[34:35], v[36:37]
	v_pk_fma_f32 v[36:37], v[34:35], v[36:37], v[34:35] neg_lo:[1,0,0] neg_hi:[1,0,0]
	s_nop 0
	v_cndmask_b32_e32 v35, v37, v41, vcc
	v_cmp_gt_f32_e32 vcc, 0, v34
	s_nop 1
	v_cndmask_b32_e32 v34, v36, v40, vcc
	v_pk_mul_f32 v[34:35], v[38:39], v[34:35]
	s_nop 0
	v_cvt_pk_bf16_f32 v151, v34, v35
	v_mad_u32_u24 v34, v210, s14, v153
	global_store_dwordx4 v34, v[148:151], s[26:27]

.LBB0_823:
	s_and_saveexec_b64 s[12:13], s[80:81]
	s_cbranch_execz .LBB0_825
	s_cmp_lt_i32 s69, s35
	s_cselect_b64 s[14:15], -1, 0
	s_cmp_ge_i32 s69, s24
	s_cselect_b64 s[48:49], -1, 0
	v_pk_fma_f32 v[36:37], v[72:73], v[98:99], v[36:37]
	s_and_b64 s[14:15], s[14:15], s[48:49]
	v_pk_fma_f32 v[38:39], v[74:75], v[100:101], v[38:39]
	v_pk_add_f32 v[36:37], v[76:77], v[36:37]
	v_pk_fma_f32 v[32:33], v[64:65], v[60:61], v[32:33]
	v_pk_add_f32 v[38:39], v[78:79], v[38:39]
	v_pk_fma_f32 v[34:35], v[66:67], v[62:63], v[34:35]
	v_pk_add_f32 v[32:33], v[68:69], v[32:33]
	v_pk_add_f32 v[34:35], v[70:71], v[34:35]
	s_mov_b32 s28, 0x3f35f0e3
	s_mov_b32 s48, 0xbe11a98e
	s_mov_b32 s8, 0x3e027906
	v_mov_b64_e32 v[148:149], v[240:241]
	s_cmp_eq_u64 s[14:15], 0
	s_cbranch_scc1 .Lffe_825
	v_cmp_eq_u32_e32 vcc, s37, v212
	v_pk_fma_f32 v[42:43], v[72:73], v[98:99], v[36:37] neg_lo:[1,0,0] neg_hi:[1,0,0]
	s_nop 0
	s_and_b64 vcc, s[14:15], vcc
	v_pk_fma_f32 v[40:41], v[58:59], v[100:101], v[38:39]
	v_cndmask_b32_e32 v37, v37, v43, vcc
	v_cndmask_b32_e32 v36, v36, v42, vcc
	v_pk_fma_f32 v[42:43], v[64:65], v[60:61], v[32:33] neg_lo:[1,0,0] neg_hi:[1,0,0]
	v_cndmask_b32_e32 v39, v39, v41, vcc
	v_cndmask_b32_e32 v38, v38, v40, vcc
	v_pk_fma_f32 v[40:41], v[56:57], v[62:63], v[34:35]
	v_cndmask_b32_e32 v33, v33, v43, vcc
	v_cndmask_b32_e32 v32, v32, v42, vcc
	v_cndmask_b32_e32 v35, v35, v41, vcc
	v_cndmask_b32_e32 v34, v34, v40, vcc
.Lffe_825:
	s_mov_b32 s14, 0xbf3a00e3
	v_fma_f32 v40, |v32|, s74, 1.0
	v_fma_f32 v41, |v33|, s74, 1.0
	v_mov_b64_e32 v[44:45], s[14:15]
	v_rcp_f32_e32 v40, v40
	v_rcp_f32_e32 v41, v41
	s_mov_b32 s14, 0x3f07dc22
	v_mul_f32_e32 v42, v32, v32
	v_pk_fma_f32 v[46:47], v[40:41], s[14:15], v[44:45] op_sel_hi:[1,0,0]
	v_mul_f32_e32 v43, v33, v33
	v_pk_fma_f32 v[46:47], v[40:41], v[46:47], s[28:29] op_sel_hi:[1,1,0]
	v_mul_f32_e32 v42, 0xbf38aa3b, v42
	v_pk_fma_f32 v[46:47], v[40:41], v[46:47], s[48:49] op_sel_hi:[1,1,0]
	v_mul_f32_e32 v43, 0xbf38aa3b, v43
	v_pk_fma_f32 v[46:47], v[40:41], v[46:47], s[8:9] op_sel_hi:[1,1,0]
	v_exp_f32_e32 v42, v42
	v_exp_f32_e32 v43, v43
	v_pk_mul_f32 v[40:41], v[40:41], v[46:47]
	v_cmp_gt_f32_e32 vcc, 0, v33
	v_pk_mul_f32 v[40:41], v[42:43], v[40:41]
	s_nop 0
	v_pk_mul_f32 v[42:43], v[32:33], v[40:41]
	v_pk_fma_f32 v[40:41], v[32:33], v[40:41], v[32:33] neg_lo:[1,0,0] neg_hi:[1,0,0]
	s_nop 0
	v_cndmask_b32_e32 v33, v41, v43, vcc
	v_cmp_gt_f32_e32 vcc, 0, v32
	s_nop 1
	v_cndmask_b32_e32 v32, v40, v42, vcc
	v_pk_mul_f32 v[32:33], v[36:37], v[32:33]
	v_cmp_gt_f32_e32 vcc, 0, v35
	v_cvt_pk_bf16_f32 v150, v32, v33
	v_fma_f32 v33, |v34|, s74, 1.0
	v_rcp_f32_e32 v36, v33
	v_fma_f32 v33, |v35|, s74, 1.0
	v_rcp_f32_e32 v37, v33
	v_mul_f32_e32 v33, v34, v34
	v_pk_fma_f32 v[42:43], v[36:37], s[14:15], v[44:45] op_sel_hi:[1,0,0]
	v_mul_f32_e32 v33, 0xbf38aa3b, v33
	v_pk_fma_f32 v[42:43], v[36:37], v[42:43], s[28:29] op_sel_hi:[1,1,0]
	v_exp_f32_e32 v40, v33
	v_pk_fma_f32 v[42:43], v[36:37], v[42:43], s[48:49] op_sel_hi:[1,1,0]
	v_mul_f32_e32 v33, v35, v35
	v_pk_fma_f32 v[42:43], v[36:37], v[42:43], s[8:9] op_sel_hi:[1,1,0]
	v_mul_f32_e32 v33, 0xbf38aa3b, v33
	v_exp_f32_e32 v41, v33
	v_pk_mul_f32 v[36:37], v[36:37], v[42:43]
	s_movk_i32 s14, 0x1600
	v_pk_mul_f32 v[36:37], v[40:41], v[36:37]
	s_nop 0
	v_pk_mul_f32 v[40:41], v[34:35], v[36:37]
	v_pk_fma_f32 v[36:37], v[34:35], v[36:37], v[34:35] neg_lo:[1,0,0] neg_hi:[1,0,0]
	s_nop 0
	v_cndmask_b32_e32 v35, v37, v41, vcc
	v_cmp_gt_f32_e32 vcc, 0, v34
	s_nop 1
	v_cndmask_b32_e32 v34, v36, v40, vcc
	v_pk_mul_f32 v[34:35], v[38:39], v[34:35]
	s_nop 0
	v_cvt_pk_bf16_f32 v151, v34, v35
	v_mad_u32_u24 v34, v200, s14, v153
	global_store_dwordx4 v34, v[148:151], s[26:27]

.LBB0_827:
	s_cmp_ge_i32 s22, s24
	v_pk_fma_f32 v[20:21], v[72:73], v[52:53], v[20:21]
	s_cselect_b64 s[14:15], -1, 0
	v_pk_fma_f32 v[22:23], v[74:75], v[54:55], v[22:23]
	v_pk_add_f32 v[20:21], v[76:77], v[20:21]
	v_pk_fma_f32 v[16:17], v[64:65], v[48:49], v[16:17]
	v_pk_add_f32 v[22:23], v[78:79], v[22:23]
	v_pk_fma_f32 v[18:19], v[66:67], v[50:51], v[18:19]
	v_pk_add_f32 v[16:17], v[68:69], v[16:17]
	v_pk_add_f32 v[18:19], v[70:71], v[18:19]
	s_mov_b32 s28, 0x3f35f0e3
	s_mov_b32 s48, 0xbe11a98e
	s_mov_b32 s8, 0x3e027906
	v_mov_b64_e32 v[148:149], v[202:203]
	s_cmp_eq_u64 s[14:15], 0
	s_cbranch_scc1 .Lffe_828
	v_cmp_eq_u32_e32 vcc, s37, v198
	v_pk_fma_f32 v[26:27], v[72:73], v[52:53], v[20:21] neg_lo:[1,0,0] neg_hi:[1,0,0]
	s_nop 0
	s_and_b64 vcc, s[14:15], vcc
	v_pk_fma_f32 v[24:25], v[58:59], v[54:55], v[22:23]
	v_cndmask_b32_e32 v21, v21, v27, vcc
	v_cndmask_b32_e32 v20, v20, v26, vcc
	v_pk_fma_f32 v[26:27], v[64:65], v[48:49], v[16:17] neg_lo:[1,0,0] neg_hi:[1,0,0]
	v_cndmask_b32_e32 v23, v23, v25, vcc
	v_cndmask_b32_e32 v22, v22, v24, vcc
	v_pk_fma_f32 v[24:25], v[56:57], v[50:51], v[18:19]
	v_cndmask_b32_e32 v17, v17, v27, vcc
	v_cndmask_b32_e32 v16, v16, v26, vcc
	v_cndmask_b32_e32 v19, v19, v25, vcc
	v_cndmask_b32_e32 v18, v18, v24, vcc
.Lffe_828:
	s_mov_b32 s14, 0xbf3a00e3
	v_fma_f32 v24, |v16|, s74, 1.0
	v_fma_f32 v25, |v17|, s74, 1.0
	v_mov_b64_e32 v[28:29], s[14:15]
	v_rcp_f32_e32 v24, v24
	v_rcp_f32_e32 v25, v25
	s_mov_b32 s14, 0x3f07dc22
	v_mul_f32_e32 v26, v16, v16
	v_pk_fma_f32 v[30:31], v[24:25], s[14:15], v[28:29] op_sel_hi:[1,0,0]
	v_mul_f32_e32 v27, v17, v17
	v_pk_fma_f32 v[30:31], v[24:25], v[30:31], s[28:29] op_sel_hi:[1,1,0]
	v_mul_f32_e32 v26, 0xbf38aa3b, v26
	v_pk_fma_f32 v[30:31], v[24:25], v[30:31], s[48:49] op_sel_hi:[1,1,0]
	v_mul_f32_e32 v27, 0xbf38aa3b, v27
	v_pk_fma_f32 v[30:31], v[24:25], v[30:31], s[8:9] op_sel_hi:[1,1,0]
	v_exp_f32_e32 v26, v26
	v_exp_f32_e32 v27, v27
	v_pk_mul_f32 v[24:25], v[24:25], v[30:31]
	v_cmp_gt_f32_e32 vcc, 0, v17
	v_pk_mul_f32 v[24:25], v[26:27], v[24:25]
	s_nop 0
	v_pk_mul_f32 v[26:27], v[16:17], v[24:25]
	v_pk_fma_f32 v[24:25], v[16:17], v[24:25], v[16:17] neg_lo:[1,0,0] neg_hi:[1,0,0]
	s_nop 0
	v_cndmask_b32_e32 v17, v25, v27, vcc
	v_cmp_gt_f32_e32 vcc, 0, v16
	s_nop 1
	v_cndmask_b32_e32 v16, v24, v26, vcc
	v_pk_mul_f32 v[16:17], v[20:21], v[16:17]
	v_cmp_gt_f32_e32 vcc, 0, v19
	v_cvt_pk_bf16_f32 v150, v16, v17
	v_fma_f32 v17, |v18|, s74, 1.0
	v_rcp_f32_e32 v20, v17
	v_fma_f32 v17, |v19|, s74, 1.0
	v_rcp_f32_e32 v21, v17
	v_mul_f32_e32 v17, v18, v18
	v_pk_fma_f32 v[26:27], v[20:21], s[14:15], v[28:29] op_sel_hi:[1,0,0]
	v_mul_f32_e32 v17, 0xbf38aa3b, v17
	v_pk_fma_f32 v[26:27], v[20:21], v[26:27], s[28:29] op_sel_hi:[1,1,0]
	v_exp_f32_e32 v24, v17
	v_pk_fma_f32 v[26:27], v[20:21], v[26:27], s[48:49] op_sel_hi:[1,1,0]
	v_mul_f32_e32 v17, v19, v19
	v_pk_fma_f32 v[26:27], v[20:21], v[26:27], s[8:9] op_sel_hi:[1,1,0]
	v_mul_f32_e32 v17, 0xbf38aa3b, v17
	v_exp_f32_e32 v25, v17
	v_pk_mul_f32 v[20:21], v[20:21], v[26:27]
	s_movk_i32 s14, 0x1600
	v_pk_mul_f32 v[20:21], v[24:25], v[20:21]
	s_nop 0
	v_pk_mul_f32 v[24:25], v[18:19], v[20:21]
	v_pk_fma_f32 v[20:21], v[18:19], v[20:21], v[18:19] neg_lo:[1,0,0] neg_hi:[1,0,0]
	s_nop 0
	v_cndmask_b32_e32 v19, v21, v25, vcc
	v_cmp_gt_f32_e32 vcc, 0, v18
	s_nop 1
	v_cndmask_b32_e32 v18, v20, v24, vcc
	v_pk_mul_f32 v[18:19], v[22:23], v[18:19]
	s_nop 0
	v_cvt_pk_bf16_f32 v151, v18, v19
	v_mad_u32_u24 v18, v105, s14, v153
	global_store_dwordx4 v18, v[148:151], s[26:27]

.LBB0_832:
	s_and_saveexec_b64 s[12:13], s[16:17]
	s_cbranch_execz .LBB0_834
	s_cmp_lt_i32 s60, s35
	s_cselect_b64 s[14:15], -1, 0
	s_cmp_ge_i32 s60, s24
	s_cselect_b64 s[16:17], -1, 0
	v_pk_fma_f32 v[12:13], v[72:73], v[44:45], v[12:13]
	s_and_b64 s[14:15], s[14:15], s[16:17]
	v_pk_fma_f32 v[14:15], v[74:75], v[46:47], v[14:15]
	v_pk_add_f32 v[12:13], v[76:77], v[12:13]
	v_pk_fma_f32 v[8:9], v[64:65], v[40:41], v[8:9]
	v_pk_add_f32 v[14:15], v[78:79], v[14:15]
	v_pk_fma_f32 v[10:11], v[66:67], v[42:43], v[10:11]
	v_pk_add_f32 v[8:9], v[68:69], v[8:9]
	v_pk_add_f32 v[10:11], v[70:71], v[10:11]
	s_mov_b32 s16, 0x3f35f0e3
	s_mov_b32 s28, 0xbe11a98e
	s_mov_b32 s8, 0x3e027906
	v_mov_b64_e32 v[148:149], v[204:205]
	s_cmp_eq_u64 s[14:15], 0
	s_cbranch_scc1 .Lffe_834
	v_cmp_eq_u32_e32 vcc, s37, v192
	v_pk_fma_f32 v[18:19], v[72:73], v[44:45], v[12:13] neg_lo:[1,0,0] neg_hi:[1,0,0]
	s_nop 0
	s_and_b64 vcc, s[14:15], vcc
	v_pk_fma_f32 v[16:17], v[58:59], v[46:47], v[14:15]
	v_cndmask_b32_e32 v13, v13, v19, vcc
	v_cndmask_b32_e32 v12, v12, v18, vcc
	v_pk_fma_f32 v[18:19], v[64:65], v[40:41], v[8:9] neg_lo:[1,0,0] neg_hi:[1,0,0]
	v_cndmask_b32_e32 v15, v15, v17, vcc
	v_cndmask_b32_e32 v14, v14, v16, vcc
	v_pk_fma_f32 v[16:17], v[56:57], v[42:43], v[10:11]
	v_cndmask_b32_e32 v9, v9, v19, vcc
	v_cndmask_b32_e32 v8, v8, v18, vcc
	v_cndmask_b32_e32 v11, v11, v17, vcc
	v_cndmask_b32_e32 v10, v10, v16, vcc
.Lffe_834:
	s_mov_b32 s14, 0xbf3a00e3
	v_fma_f32 v16, |v8|, s74, 1.0
	v_fma_f32 v17, |v9|, s74, 1.0
	v_mov_b64_e32 v[20:21], s[14:15]
	v_rcp_f32_e32 v16, v16
	v_rcp_f32_e32 v17, v17
	s_mov_b32 s14, 0x3f07dc22
	v_mul_f32_e32 v18, v8, v8
	v_pk_fma_f32 v[22:23], v[16:17], s[14:15], v[20:21] op_sel_hi:[1,0,0]
	v_mul_f32_e32 v19, v9, v9
	v_pk_fma_f32 v[22:23], v[16:17], v[22:23], s[16:17] op_sel_hi:[1,1,0]
	v_mul_f32_e32 v18, 0xbf38aa3b, v18
	v_pk_fma_f32 v[22:23], v[16:17], v[22:23], s[28:29] op_sel_hi:[1,1,0]
	v_mul_f32_e32 v19, 0xbf38aa3b, v19
	v_pk_fma_f32 v[22:23], v[16:17], v[22:23], s[8:9] op_sel_hi:[1,1,0]
	v_exp_f32_e32 v18, v18
	v_exp_f32_e32 v19, v19
	v_pk_mul_f32 v[16:17], v[16:17], v[22:23]
	v_cmp_gt_f32_e32 vcc, 0, v9
	v_pk_mul_f32 v[16:17], v[18:19], v[16:17]
	s_nop 0
	v_pk_mul_f32 v[18:19], v[8:9], v[16:17]
	v_pk_fma_f32 v[16:17], v[8:9], v[16:17], v[8:9] neg_lo:[1,0,0] neg_hi:[1,0,0]
	s_nop 0
	v_cndmask_b32_e32 v9, v17, v19, vcc
	v_cmp_gt_f32_e32 vcc, 0, v8
	s_nop 1
	v_cndmask_b32_e32 v8, v16, v18, vcc
	v_pk_mul_f32 v[8:9], v[12:13], v[8:9]
	v_cmp_gt_f32_e32 vcc, 0, v11
	v_cvt_pk_bf16_f32 v150, v8, v9
	v_fma_f32 v9, |v10|, s74, 1.0
	v_rcp_f32_e32 v12, v9
	v_fma_f32 v9, |v11|, s74, 1.0
	v_rcp_f32_e32 v13, v9
	v_mul_f32_e32 v9, v10, v10
	v_pk_fma_f32 v[18:19], v[12:13], s[14:15], v[20:21] op_sel_hi:[1,0,0]
	v_mul_f32_e32 v9, 0xbf38aa3b, v9
	v_pk_fma_f32 v[18:19], v[12:13], v[18:19], s[16:17] op_sel_hi:[1,1,0]
	v_exp_f32_e32 v16, v9
	v_pk_fma_f32 v[18:19], v[12:13], v[18:19], s[28:29] op_sel_hi:[1,1,0]
	v_mul_f32_e32 v9, v11, v11
	v_pk_fma_f32 v[18:19], v[12:13], v[18:19], s[8:9] op_sel_hi:[1,1,0]
	v_mul_f32_e32 v9, 0xbf38aa3b, v9
	v_exp_f32_e32 v17, v9
	v_pk_mul_f32 v[12:13], v[12:13], v[18:19]
	s_movk_i32 s14, 0x1600
	v_pk_mul_f32 v[12:13], v[16:17], v[12:13]
	s_nop 0
	v_pk_mul_f32 v[16:17], v[10:11], v[12:13]
	v_pk_fma_f32 v[12:13], v[10:11], v[12:13], v[10:11] neg_lo:[1,0,0] neg_hi:[1,0,0]
	s_nop 0
	v_cndmask_b32_e32 v11, v13, v17, vcc
	v_cmp_gt_f32_e32 vcc, 0, v10
	s_nop 1
	v_cndmask_b32_e32 v10, v12, v16, vcc
	v_pk_mul_f32 v[10:11], v[14:15], v[10:11]
	s_nop 0
	v_cvt_pk_bf16_f32 v151, v10, v11
	v_mad_u32_u24 v10, v97, s14, v153
	global_store_dwordx4 v10, v[148:151], s[26:27]

.LBB0_838:
	s_and_saveexec_b64 s[12:13], s[18:19]
	s_cbranch_execz .LBB0_840
	s_cmp_lt_i32 s64, s35
	s_cselect_b64 s[14:15], -1, 0
	s_cmp_ge_i32 s64, s24
	s_cselect_b64 s[16:17], -1, 0
	v_pk_fma_f32 v[4:5], v[72:73], v[36:37], v[4:5]
	s_and_b64 s[14:15], s[14:15], s[16:17]
	v_pk_fma_f32 v[6:7], v[74:75], v[38:39], v[6:7]
	v_pk_add_f32 v[4:5], v[76:77], v[4:5]
	v_pk_fma_f32 v[0:1], v[64:65], v[32:33], v[0:1]
	v_pk_add_f32 v[6:7], v[78:79], v[6:7]
	v_pk_fma_f32 v[2:3], v[66:67], v[34:35], v[2:3]
	v_pk_add_f32 v[0:1], v[68:69], v[0:1]
	v_pk_add_f32 v[2:3], v[70:71], v[2:3]
	s_mov_b32 s16, 0x3f35f0e3
	s_mov_b32 s18, 0xbe11a98e
	s_mov_b32 s8, 0x3e027906
	v_mov_b64_e32 v[148:149], v[206:207]
	s_cmp_eq_u64 s[14:15], 0
	s_cbranch_scc1 .Lffe_840
	v_cmp_eq_u32_e32 vcc, s37, v147
	v_pk_fma_f32 v[10:11], v[72:73], v[36:37], v[4:5] neg_lo:[1,0,0] neg_hi:[1,0,0]
	s_nop 0
	s_and_b64 vcc, s[14:15], vcc
	v_pk_fma_f32 v[8:9], v[58:59], v[38:39], v[6:7]
	v_cndmask_b32_e32 v5, v5, v11, vcc
	v_cndmask_b32_e32 v4, v4, v10, vcc
	v_pk_fma_f32 v[10:11], v[64:65], v[32:33], v[0:1] neg_lo:[1,0,0] neg_hi:[1,0,0]
	v_cndmask_b32_e32 v7, v7, v9, vcc
	v_cndmask_b32_e32 v6, v6, v8, vcc
	v_pk_fma_f32 v[8:9], v[56:57], v[34:35], v[2:3]
	v_cndmask_b32_e32 v1, v1, v11, vcc
	v_cndmask_b32_e32 v0, v0, v10, vcc
	v_cndmask_b32_e32 v3, v3, v9, vcc
	v_cndmask_b32_e32 v2, v2, v8, vcc
.Lffe_840:
	s_mov_b32 s14, 0xbf3a00e3
	v_fma_f32 v8, |v0|, s74, 1.0
	v_fma_f32 v9, |v1|, s74, 1.0
	v_mov_b64_e32 v[12:13], s[14:15]
	v_rcp_f32_e32 v8, v8
	v_rcp_f32_e32 v9, v9
	s_mov_b32 s14, 0x3f07dc22
	v_mul_f32_e32 v10, v0, v0
	v_pk_fma_f32 v[14:15], v[8:9], s[14:15], v[12:13] op_sel_hi:[1,0,0]
	v_mul_f32_e32 v11, v1, v1
	v_pk_fma_f32 v[14:15], v[8:9], v[14:15], s[16:17] op_sel_hi:[1,1,0]
	v_mul_f32_e32 v10, 0xbf38aa3b, v10
	v_pk_fma_f32 v[14:15], v[8:9], v[14:15], s[18:19] op_sel_hi:[1,1,0]
	v_mul_f32_e32 v11, 0xbf38aa3b, v11
	v_pk_fma_f32 v[14:15], v[8:9], v[14:15], s[8:9] op_sel_hi:[1,1,0]
	v_exp_f32_e32 v10, v10
	v_exp_f32_e32 v11, v11
	v_pk_mul_f32 v[8:9], v[8:9], v[14:15]
	v_cmp_gt_f32_e32 vcc, 0, v1
	v_pk_mul_f32 v[8:9], v[10:11], v[8:9]
	s_nop 0
	v_pk_mul_f32 v[10:11], v[0:1], v[8:9]
	v_pk_fma_f32 v[8:9], v[0:1], v[8:9], v[0:1] neg_lo:[1,0,0] neg_hi:[1,0,0]
	s_nop 0
	v_cndmask_b32_e32 v1, v9, v11, vcc
	v_cmp_gt_f32_e32 vcc, 0, v0
	s_nop 1
	v_cndmask_b32_e32 v0, v8, v10, vcc
	v_pk_mul_f32 v[0:1], v[4:5], v[0:1]
	v_cmp_gt_f32_e32 vcc, 0, v3
	v_cvt_pk_bf16_f32 v150, v0, v1
	v_fma_f32 v1, |v2|, s74, 1.0
	v_rcp_f32_e32 v4, v1
	v_fma_f32 v1, |v3|, s74, 1.0
	v_rcp_f32_e32 v5, v1
	v_mul_f32_e32 v1, v2, v2
	v_pk_fma_f32 v[10:11], v[4:5], s[14:15], v[12:13] op_sel_hi:[1,0,0]
	v_mul_f32_e32 v1, 0xbf38aa3b, v1
	v_pk_fma_f32 v[10:11], v[4:5], v[10:11], s[16:17] op_sel_hi:[1,1,0]
	v_exp_f32_e32 v8, v1
	v_pk_fma_f32 v[10:11], v[4:5], v[10:11], s[18:19] op_sel_hi:[1,1,0]
	v_mul_f32_e32 v1, v3, v3
	v_pk_fma_f32 v[10:11], v[4:5], v[10:11], s[8:9] op_sel_hi:[1,1,0]
	v_mul_f32_e32 v1, 0xbf38aa3b, v1
	v_exp_f32_e32 v9, v1
	v_pk_mul_f32 v[4:5], v[4:5], v[10:11]
	s_movk_i32 s14, 0x1600
	v_pk_mul_f32 v[4:5], v[8:9], v[4:5]
	s_nop 0
	v_pk_mul_f32 v[8:9], v[2:3], v[4:5]
	v_pk_fma_f32 v[4:5], v[2:3], v[4:5], v[2:3] neg_lo:[1,0,0] neg_hi:[1,0,0]
	s_nop 0
	v_cndmask_b32_e32 v3, v5, v9, vcc
	v_cmp_gt_f32_e32 vcc, 0, v2
	s_nop 1
	v_cndmask_b32_e32 v2, v4, v8, vcc
	v_pk_mul_f32 v[2:3], v[6:7], v[2:3]
	s_nop 0
	v_cvt_pk_bf16_f32 v151, v2, v3
	v_mad_u32_u24 v2, v146, s14, v153
	global_store_dwordx4 v2, v[148:151], s[26:27]

.LBB0_846:
	s_cmp_lt_i32 s66, s35
	s_cselect_b64 s[14:15], -1, 0
	s_cmp_ge_i32 s66, s24
	s_cselect_b64 s[16:17], -1, 0
	v_pk_fma_f32 v[4:5], v[72:73], v[28:29], v[4:5]
	s_and_b64 s[14:15], s[14:15], s[16:17]
	v_pk_fma_f32 v[6:7], v[74:75], v[30:31], v[6:7]
	v_pk_add_f32 v[4:5], v[76:77], v[4:5]
	v_pk_fma_f32 v[0:1], v[64:65], v[24:25], v[0:1]
	v_pk_add_f32 v[6:7], v[78:79], v[6:7]
	v_pk_fma_f32 v[2:3], v[66:67], v[26:27], v[2:3]
	v_pk_add_f32 v[0:1], v[68:69], v[0:1]
	v_pk_add_f32 v[2:3], v[70:71], v[2:3]
	s_mov_b32 s16, 0x3f35f0e3
	s_mov_b32 s18, 0xbe11a98e
	s_mov_b32 s8, 0x3e027906
	v_mov_b64_e32 v[148:149], v[208:209]
	s_cmp_eq_u64 s[14:15], 0
	s_cbranch_scc1 .Lffe_846
	v_cmp_eq_u32_e32 vcc, s37, v134
	v_pk_fma_f32 v[10:11], v[72:73], v[28:29], v[4:5] neg_lo:[1,0,0] neg_hi:[1,0,0]
	s_nop 0
	s_and_b64 vcc, s[14:15], vcc
	v_pk_fma_f32 v[8:9], v[58:59], v[30:31], v[6:7]
	v_cndmask_b32_e32 v5, v5, v11, vcc
	v_cndmask_b32_e32 v4, v4, v10, vcc
	v_pk_fma_f32 v[10:11], v[64:65], v[24:25], v[0:1] neg_lo:[1,0,0] neg_hi:[1,0,0]
	v_cndmask_b32_e32 v7, v7, v9, vcc
	v_cndmask_b32_e32 v6, v6, v8, vcc
	v_pk_fma_f32 v[8:9], v[56:57], v[26:27], v[2:3]
	v_cndmask_b32_e32 v1, v1, v11, vcc
	v_cndmask_b32_e32 v0, v0, v10, vcc
	v_cndmask_b32_e32 v3, v3, v9, vcc
	v_cndmask_b32_e32 v2, v2, v8, vcc
.Lffe_846:
	s_mov_b32 s14, 0xbf3a00e3
	v_fma_f32 v8, |v0|, s74, 1.0
	v_fma_f32 v9, |v1|, s74, 1.0
	v_mov_b64_e32 v[12:13], s[14:15]
	v_rcp_f32_e32 v8, v8
	v_rcp_f32_e32 v9, v9
	s_mov_b32 s14, 0x3f07dc22
	v_mul_f32_e32 v10, v0, v0
	v_pk_fma_f32 v[14:15], v[8:9], s[14:15], v[12:13] op_sel_hi:[1,0,0]
	v_mul_f32_e32 v11, v1, v1
	v_pk_fma_f32 v[14:15], v[8:9], v[14:15], s[16:17] op_sel_hi:[1,1,0]
	v_mul_f32_e32 v10, 0xbf38aa3b, v10
	v_pk_fma_f32 v[14:15], v[8:9], v[14:15], s[18:19] op_sel_hi:[1,1,0]
	v_mul_f32_e32 v11, 0xbf38aa3b, v11
	v_pk_fma_f32 v[14:15], v[8:9], v[14:15], s[8:9] op_sel_hi:[1,1,0]
	v_exp_f32_e32 v10, v10
	v_exp_f32_e32 v11, v11
	v_pk_mul_f32 v[8:9], v[8:9], v[14:15]
	v_cmp_gt_f32_e32 vcc, 0, v1
	v_pk_mul_f32 v[8:9], v[10:11], v[8:9]
	s_nop 0
	v_pk_mul_f32 v[10:11], v[0:1], v[8:9]
	v_pk_fma_f32 v[8:9], v[0:1], v[8:9], v[0:1] neg_lo:[1,0,0] neg_hi:[1,0,0]
	s_nop 0
	v_cndmask_b32_e32 v1, v9, v11, vcc
	v_cmp_gt_f32_e32 vcc, 0, v0
	s_nop 1
	v_cndmask_b32_e32 v0, v8, v10, vcc
	v_pk_mul_f32 v[0:1], v[4:5], v[0:1]
	v_cmp_gt_f32_e32 vcc, 0, v3
	v_cvt_pk_bf16_f32 v150, v0, v1
	v_fma_f32 v1, |v2|, s74, 1.0
	v_rcp_f32_e32 v4, v1
	v_fma_f32 v1, |v3|, s74, 1.0
	v_rcp_f32_e32 v5, v1
	v_mul_f32_e32 v1, v2, v2
	v_pk_fma_f32 v[10:11], v[4:5], s[14:15], v[12:13] op_sel_hi:[1,0,0]
	v_mul_f32_e32 v1, 0xbf38aa3b, v1
	v_pk_fma_f32 v[10:11], v[4:5], v[10:11], s[16:17] op_sel_hi:[1,1,0]
	v_exp_f32_e32 v8, v1
	v_pk_fma_f32 v[10:11], v[4:5], v[10:11], s[18:19] op_sel_hi:[1,1,0]
	v_mul_f32_e32 v1, v3, v3
	v_pk_fma_f32 v[10:11], v[4:5], v[10:11], s[8:9] op_sel_hi:[1,1,0]
	v_mul_f32_e32 v1, 0xbf38aa3b, v1
	v_exp_f32_e32 v9, v1
	v_pk_mul_f32 v[4:5], v[4:5], v[10:11]
	s_movk_i32 s14, 0x1600
	v_pk_mul_f32 v[4:5], v[8:9], v[4:5]
	s_nop 0
	v_pk_mul_f32 v[8:9], v[2:3], v[4:5]
	v_pk_fma_f32 v[4:5], v[2:3], v[4:5], v[2:3] neg_lo:[1,0,0] neg_hi:[1,0,0]
	s_nop 0
	v_cndmask_b32_e32 v3, v5, v9, vcc
	v_cmp_gt_f32_e32 vcc, 0, v2
	s_nop 1
	v_cndmask_b32_e32 v2, v4, v8, vcc
	v_pk_mul_f32 v[2:3], v[6:7], v[2:3]
	s_nop 0
	v_cvt_pk_bf16_f32 v151, v2, v3
	v_mad_u32_u24 v2, v124, s14, v153
	global_store_dwordx4 v2, v[148:151], s[26:27]
	s_or_b64 exec, exec, s[12:13]
	s_andn2_b64 vcc, exec, s[46:47]
	s_mov_b64 s[12:13], -1
	s_cbranch_vccnz .LBB0_736
